# dilated attention fast mask paths write the logits in place (no copy-back through temporaries), on the full bundle
# speedup vs baseline: 1.0109x; 1.0109x over previous
.LBB0_751:
	s_andn2_b64 vcc, exec, s[40:41]
	s_cbranch_vccnz .LBB0_753
	v_add_f32_e32 v112, v196, v112
	v_add_f32_e32 v96, v196, v96
	v_add_f32_e32 v113, v197, v113
	v_add_f32_e32 v97, v197, v97
	v_add_f32_e32 v114, v198, v114
	v_add_f32_e32 v98, v198, v98
	v_add_f32_e32 v115, v199, v115
	v_add_f32_e32 v99, v199, v99
	v_add_f32_e32 v116, v200, v116
	v_add_f32_e32 v100, v200, v100
	v_add_f32_e32 v117, v201, v117
	v_add_f32_e32 v101, v201, v101
	v_add_f32_e32 v118, v202, v118
	v_add_f32_e32 v102, v202, v102
	v_add_f32_e32 v119, v203, v119
	v_add_f32_e32 v103, v203, v103
	v_add_f32_e32 v120, v196, v120
	v_add_f32_e32 v104, v196, v104
	v_add_f32_e32 v121, v204, v121
	v_add_f32_e32 v105, v204, v105
	v_add_f32_e32 v122, v205, v122
	v_add_f32_e32 v106, v205, v106
	v_add_f32_e32 v123, v206, v123
	v_add_f32_e32 v107, v206, v107
	v_add_f32_e32 v124, v200, v124
	v_add_f32_e32 v108, v200, v108
	v_add_f32_e32 v125, v207, v125
	v_add_f32_e32 v109, v207, v109
	v_add_f32_e32 v126, v209, v126
	v_add_f32_e32 v110, v209, v110
	v_add_f32_e32 v127, v210, v127
	v_add_f32_e32 v111, v210, v111
	s_branch .LBB0_757

.LBB0_754:
	s_andn2_b64 vcc, exec, s[40:41]
	s_cbranch_vccnz .LBB0_756
	v_cndmask_b32_e64 v112, v16, v112, s[4:5]
	v_cndmask_b32_e64 v96, v16, v96, s[4:5]
	v_cndmask_b32_e64 v113, v16, v113, s[6:7]
	v_cndmask_b32_e64 v97, v16, v97, s[6:7]
	v_cndmask_b32_e64 v114, v16, v114, s[8:9]
	v_cndmask_b32_e64 v98, v16, v98, s[8:9]
	v_cndmask_b32_e64 v115, v16, v115, s[10:11]
	v_cndmask_b32_e64 v99, v16, v99, s[10:11]
	v_cndmask_b32_e64 v116, v16, v116, s[14:15]
	v_cndmask_b32_e64 v100, v16, v100, s[14:15]
	v_cndmask_b32_e64 v117, v16, v117, s[16:17]
	v_cndmask_b32_e64 v101, v16, v101, s[16:17]
	v_cndmask_b32_e64 v118, v16, v118, s[18:19]
	v_cndmask_b32_e64 v102, v16, v102, s[18:19]
	v_cndmask_b32_e64 v119, v16, v119, s[20:21]
	v_cndmask_b32_e64 v103, v16, v103, s[20:21]
	v_cndmask_b32_e64 v120, v16, v120, s[4:5]
	v_cndmask_b32_e64 v104, v16, v104, s[4:5]
	v_cndmask_b32_e64 v121, v16, v121, s[22:23]
	v_cndmask_b32_e64 v105, v16, v105, s[22:23]
	v_cndmask_b32_e64 v122, v16, v122, s[24:25]
	v_cndmask_b32_e64 v106, v16, v106, s[24:25]
	v_cndmask_b32_e64 v123, v16, v123, s[26:27]
	v_cndmask_b32_e64 v107, v16, v107, s[26:27]
	v_cndmask_b32_e64 v124, v16, v124, s[14:15]
	v_cndmask_b32_e64 v108, v16, v108, s[14:15]
	v_cndmask_b32_e64 v125, v16, v125, s[28:29]
	v_cndmask_b32_e64 v109, v16, v109, s[28:29]
	v_cndmask_b32_e64 v126, v16, v126, s[30:31]
	v_cndmask_b32_e64 v110, v16, v110, s[30:31]
	v_cndmask_b32_e64 v127, v16, v127, s[34:35]
	v_cndmask_b32_e64 v111, v16, v111, s[34:35]
	s_branch .LBB0_757

.LBB0_761:
	s_andn2_b64 vcc, exec, s[40:41]
	s_cbranch_vccnz .LBB0_763
	v_add_f32_e32 v80, v196, v80
	v_add_f32_e32 v64, v196, v64
	v_add_f32_e32 v81, v197, v81
	v_add_f32_e32 v65, v197, v65
	v_add_f32_e32 v82, v198, v82
	v_add_f32_e32 v66, v198, v66
	v_add_f32_e32 v83, v199, v83
	v_add_f32_e32 v67, v199, v67
	v_add_f32_e32 v84, v200, v84
	v_add_f32_e32 v68, v200, v68
	v_add_f32_e32 v85, v201, v85
	v_add_f32_e32 v69, v201, v69
	v_add_f32_e32 v86, v202, v86
	v_add_f32_e32 v70, v202, v70
	v_add_f32_e32 v87, v203, v87
	v_add_f32_e32 v71, v203, v71
	v_add_f32_e32 v88, v196, v88
	v_add_f32_e32 v72, v196, v72
	v_add_f32_e32 v89, v204, v89
	v_add_f32_e32 v73, v204, v73
	v_add_f32_e32 v90, v205, v90
	v_add_f32_e32 v74, v205, v74
	v_add_f32_e32 v91, v206, v91
	v_add_f32_e32 v75, v206, v75
	v_add_f32_e32 v92, v200, v92
	v_add_f32_e32 v76, v200, v76
	v_add_f32_e32 v93, v207, v93
	v_add_f32_e32 v77, v207, v77
	v_add_f32_e32 v94, v209, v94
	v_add_f32_e32 v78, v209, v78
	v_add_f32_e32 v95, v210, v95
	v_add_f32_e32 v79, v210, v79
	s_branch .LBB0_767

.LBB0_764:
	s_andn2_b64 vcc, exec, s[40:41]
	s_cbranch_vccnz .LBB0_766
	v_cndmask_b32_e64 v80, v16, v80, s[4:5]
	v_cndmask_b32_e64 v64, v16, v64, s[4:5]
	v_cndmask_b32_e64 v81, v16, v81, s[6:7]
	v_cndmask_b32_e64 v65, v16, v65, s[6:7]
	v_cndmask_b32_e64 v82, v16, v82, s[8:9]
	v_cndmask_b32_e64 v66, v16, v66, s[8:9]
	v_cndmask_b32_e64 v83, v16, v83, s[10:11]
	v_cndmask_b32_e64 v67, v16, v67, s[10:11]
	v_cndmask_b32_e64 v84, v16, v84, s[14:15]
	v_cndmask_b32_e64 v68, v16, v68, s[14:15]
	v_cndmask_b32_e64 v85, v16, v85, s[16:17]
	v_cndmask_b32_e64 v69, v16, v69, s[16:17]
	v_cndmask_b32_e64 v86, v16, v86, s[18:19]
	v_cndmask_b32_e64 v70, v16, v70, s[18:19]
	v_cndmask_b32_e64 v87, v16, v87, s[20:21]
	v_cndmask_b32_e64 v71, v16, v71, s[20:21]
	v_cndmask_b32_e64 v88, v16, v88, s[4:5]
	v_cndmask_b32_e64 v72, v16, v72, s[4:5]
	v_cndmask_b32_e64 v89, v16, v89, s[22:23]
	v_cndmask_b32_e64 v73, v16, v73, s[22:23]
	v_cndmask_b32_e64 v90, v16, v90, s[24:25]
	v_cndmask_b32_e64 v74, v16, v74, s[24:25]
	v_cndmask_b32_e64 v91, v16, v91, s[26:27]
	v_cndmask_b32_e64 v75, v16, v75, s[26:27]
	v_cndmask_b32_e64 v92, v16, v92, s[14:15]
	v_cndmask_b32_e64 v76, v16, v76, s[14:15]
	v_cndmask_b32_e64 v93, v16, v93, s[28:29]
	v_cndmask_b32_e64 v77, v16, v77, s[28:29]
	v_cndmask_b32_e64 v94, v16, v94, s[30:31]
	v_cndmask_b32_e64 v78, v16, v78, s[30:31]
	v_cndmask_b32_e64 v95, v16, v95, s[34:35]
	v_cndmask_b32_e64 v79, v16, v79, s[34:35]
	s_branch .LBB0_767
